# v051 + static s_setprio 1 for waves 4-7 during the two scan phases (reset at the seams)
# speedup vs baseline: 1.0056x; 1.0056x over previous
; #define SEAM(k) do { if ((k) + 1 < hi) xcd_barrier(xbar); } while (0)
; __device__ __forceinline__ void phase_scan1(const Params& p, unsigned char* lds) {
;     const int tid = threadIdx.x, lane = tid & 63, w = tid >> 6;
;     const unsigned short* Gp = (const unsigned short*)(p.ws + WS_G); const bf16_t* Vp = (const bf16_t*)(p.ws + WS_V);
;     for (int item = blockIdx.x; item < 256; item += gridDim.x) {
;         const int seq = item >> 3, seg = item & 7, dir = seq >> 4, b = (seq >> 3) & 1, h = seq & 7;
;         f32x4 S[8];
; #pragma unroll
;         for (int kt = 0; kt < 8; ++kt) S[kt] = (f32x4){0.f, 0.f, 0.f, 0.f};
;         f32x2 dtot = {0.f, 0.f};
;         if (seg < 7) scan_run<false>(lds, Gp, Vp, nullptr, nullptr, dir ? b * SEQ + SEQ - 1 : b * SEQ, dir ? -1 : 1, seg * 32, 32, dir * 1024 + h * 128, h * 128, S, dtot);
;         else scan_run<false>(lds, Gp, Vp, nullptr, nullptr, dir ? T + b * CTXL + CTXL - 1 : T + b * CTXL, dir ? -1 : 1, 0, 4, dir * 1024 + h * 128, h * 128, S, dtot);
; __global__ void __launch_bounds__(512, 2) hymba_fwd(Params p) {
;     ...
;     if (IN(3)) { phase_scan1(p, shm); SEAM(3); }
.LBB0_335:
	s_cmp_lt_i32 s60, 4
	s_cselect_b64 s[0:1], -1, 0
	s_cmp_gt_i32 s61, 3
	s_cselect_b64 s[2:3], -1, 0
	s_and_b64 s[0:1], s[0:1], s[2:3]
	s_andn2_b64 vcc, exec, s[0:1]
	s_cbranch_vccnz .LBB0_459
	s_cmpk_gt_i32 s12, 0xff
	s_cbranch_scc1 .LBB0_405
	v_readfirstlane_b32 s98, v242
	s_cmpk_gt_u32 s98, 0xff
	s_cbranch_scc0 .Lprio_scan1
	s_setprio 1
.Lprio_scan1:
	s_add_u32 s6, s58, 0x23d86000
	s_addc_u32 s7, s59, 0
	s_add_u32 s8, s58, 0xfc86000
	v_and_b32_e32 v0, 63, v242
	v_lshlrev_b32_e32 v1, 1, v242
	s_addc_u32 s9, s59, 0
	v_and_b32_e32 v2, 0x7e, v1
	s_add_i32 s0, 0, 0x13c00
	v_lshlrev_b32_e32 v1, 3, v0
	v_add_u32_e32 v85, s0, v1
	s_movk_i32 s0, 0x120
	v_mad_u32_u24 v138, v0, s0, 0
	s_add_i32 s0, 0, 0x14c00
	s_add_i32 s1, 0, 0x14e00
	v_add_u32_e32 v139, s0, v1
	v_add_u32_e32 v140, s1, v1
	v_and_b32_e32 v1, 48, v242
	v_mov_b32_e32 v83, 0
	v_add_u32_e32 v142, s0, v1
	v_add_u32_e32 v84, 0, v1
	v_lshlrev_b32_e32 v82, 1, v2
	v_lshlrev_b32_e32 v1, 7, v242
	v_lshl_add_u64 v[86:87], s[6:7], 0, v[82:83]
	v_lshl_add_u64 v[88:89], s[8:9], 0, v[82:83]
	v_and_b32_e32 v82, 0x1e000, v1
	v_lshl_add_u64 v[10:11], s[58:59], 0, v[82:83]
	s_mov_b64 s[0:1], 0x6a66000
	v_lshlrev_b32_e32 v82, 3, v242
	v_lshlrev_b32_e32 v4, 1, v0
	v_and_b32_e32 v141, 15, v242
	s_waitcnt lgkmcnt(0)
	s_movk_i32 s38, 0x90
	v_or_b32_e32 v6, 0x3c0, v242
	v_or_b32_e32 v8, 0x7c0, v242
	v_lshl_add_u64 v[90:91], v[10:11], 0, s[0:1]
	v_lshl_add_u64 v[10:11], s[58:59], 0, v[82:83]
	s_mov_b64 s[0:1], 0x7a66000
	s_mov_b32 s21, 0
	v_mad_u32_u24 v143, v141, s38, v84
	v_cmp_gt_u32_e64 s[2:3], 64, v242
	v_lshl_add_u64 v[92:93], v[10:11], 0, s[0:1]
	v_lshlrev_b32_e32 v94, 1, v2
	v_lshlrev_b32_e32 v96, 1, v4
	s_mov_b32 s39, 0x5040100
	s_mov_b32 s40, 0x7060302
	s_mov_b32 s41, 0x800000
	s_mov_b32 s42, 0x3f317217
	s_mov_b32 s43, 0x7f800000
	v_lshlrev_b32_e32 v82, 2, v0
	v_lshlrev_b32_e32 v98, 2, v6
	s_movk_i32 s44, 0x1000
	v_lshlrev_b32_e32 v100, 2, v8
	v_mov_b32_e32 v144, 0x41b17218
	s_mov_b32 s26, s12
	s_branch .LBB0_339

; __device__ __forceinline__ unsigned xb_ld(unsigned* p)              { return __hip_atomic_load(p, __ATOMIC_RELAXED, __HIP_MEMORY_SCOPE_AGENT); }
; __device__ __forceinline__ unsigned xb_add(unsigned* p, unsigned v) { return __hip_atomic_fetch_add(p, v, __ATOMIC_RELAXED, __HIP_MEMORY_SCOPE_AGENT); }
; __device__ __forceinline__ void xcd_barrier_complete(unsigned* bar, unsigned x, unsigned& nloc, unsigned& nx) {
;     const unsigned G = gridDim.x * gridDim.y * gridDim.z;
;     unsigned sum, cnt, mine, sp = 0u;
;     for (;;) {
;         sum = 0u; cnt = 0u; mine = 0u;
; #pragma unroll
;         for (unsigned j = 0; j < 16; ++j) { const unsigned c = xb_ld(&bar[XB_XCNT(j)]); sum += c; cnt += (c > 0u) ? 1u : 0u; mine = (j == x) ? c : mine; }
;         if (sum == G) break;
;         __builtin_amdgcn_s_sleep(1);
;         if ((++sp & 255u) == 0u) { if (xb_ld(&bar[XB_TMO])) break; if (sp > XB_SPIN_CAP) { atomicAdd(&bar[XB_TMO], 1u); break; } }
;     }
;     nloc = mine > 0u ? mine : 1u; nx = cnt > 0u ? cnt : 1u;
; }
; __device__ __forceinline__ void xcd_barrier(const XcdBarrier& b) {
;     asm volatile("s_waitcnt vmcnt(0)" ::: "memory");
;     __syncthreads();
;     if (threadIdx.x == 0) {
;         unsigned* bar = b.bar;
;         __builtin_amdgcn_s_waitcnt(0);
;         unsigned nloc = b.st[0], nx = b.st[1];
;         if (nloc == 0u) { xcd_barrier_complete(bar, b.x, nloc, nx); b.st[0] = nloc; b.st[1] = nx; }
;         const unsigned old = xb_add(&bar[XB_XSUB(b.x)], 1u);
.LBB0_405:
	s_setprio 0
	s_cmp_lt_i32 s61, 5
	s_cbranch_scc1 .LBB0_459
	s_waitcnt vmcnt(0)
	s_waitcnt vmcnt(0) lgkmcnt(0)
	s_barrier
	s_and_saveexec_b64 s[0:1], s[80:81]
	s_cbranch_execz .LBB0_458
	s_add_i32 s2, 0, 0x20000
	v_mov_b32_e32 v0, s2
	s_waitcnt vmcnt(0) expcnt(0) lgkmcnt(0)
	ds_read_b32 v2, v0
	s_add_i32 s2, 0, 0x20004
	v_mov_b32_e32 v0, s2
	ds_read_b32 v0, v0
	s_waitcnt lgkmcnt(1)
	v_cmp_ne_u32_e32 vcc, 0, v2
	s_cbranch_vccnz .LBB0_422
	s_add_u32 s2, s58, 0x35d86200
	s_addc_u32 s3, s59, 0
	s_add_u32 s4, s58, 0x35d86400
	s_addc_u32 s5, s59, 0
	s_add_u32 s6, s58, 0x35d86500
	s_addc_u32 s7, s59, 0
	s_add_u32 s8, s58, 0x35d86600
	s_addc_u32 s9, s59, 0
	s_add_u32 s20, s58, 0x35d86700
	s_addc_u32 s21, s59, 0
	s_add_u32 s26, s58, 0x35d86800
	s_addc_u32 s27, s59, 0
	s_add_u32 s28, s58, 0x35d86900
	s_addc_u32 s29, s59, 0
	s_add_u32 s30, s58, 0x35d86a00
	s_addc_u32 s31, s59, 0
	s_add_u32 s34, s58, 0x35d86b00
	s_addc_u32 s35, s59, 0
	s_add_u32 s38, s58, 0x35d86c00
	s_addc_u32 s39, s59, 0
	s_add_u32 s40, s58, 0x35d86d00
	s_addc_u32 s41, s59, 0
	s_add_u32 s42, s58, 0x35d86e00
	s_addc_u32 s43, s59, 0
	s_add_u32 s44, s58, 0x35d86f00
	s_addc_u32 s45, s59, 0
	s_add_u32 s46, s58, 0x35d87000
	s_addc_u32 s47, s59, 0
	s_add_u32 s48, s58, 0x35d87100
	s_addc_u32 s49, s59, 0
	s_add_u32 s50, s58, 0x35d87200
	s_addc_u32 s51, s59, 0
	s_mul_i32 s72, s63, s78
	s_add_u32 s64, s58, 0x35d87300
	s_mul_i32 s72, s72, s62
	s_addc_u32 s65, s59, 0
	s_mov_b32 s73, 1
	v_mov_b32_e32 v16, 0
	s_branch .LBB0_410

; __device__ __forceinline__ void phase_scan2(const Params& p, unsigned char* lds) {
;     const int tid = threadIdx.x, lane = tid & 63, w = tid >> 6, q = lane >> 4;
;     const unsigned short* Gp = (const unsigned short*)(p.ws + WS_G); const bf16_t* Vp = (const bf16_t*)(p.ws + WS_V); const bf16_t* Qp = (const bf16_t*)(p.ws + WS_Q);
;     for (int item = blockIdx.x; item < 256; item += gridDim.x) {
;         const int seq = item >> 3, seg = item & 7, dir = seq >> 4, b = (seq >> 3) & 1, h = seq & 7;
;         f32x4 S[8];
;         const float* segb = (const float*)(p.ws + WS_SEG) + ((size_t)(seq * 8) * 8 + w) * 2048; const float* decb = (const float*)(p.ws + WS_SEGDEC) + (seq * 8) * 128;
; #pragma unroll
;         for (int kt = 0; kt < 8; ++kt)
; #pragma unroll
;             for (int j = 0; j < 4; ++j) S[kt][j] = segb[(size_t)7 * 8 * 2048 + (kt * 4 + j) * 64 + lane];
;         int s = 0;
;         for (; s + 1 < seg; s += 2) {
;             f32x4 La[8], Lb[8], Da[8], Db[8];
; #pragma unroll
;             for (int kt = 0; kt < 8; ++kt) { Da[kt] = *(const f32x4*)(decb + s * 128 + 16 * kt + 4 * q); Db[kt] = *(const f32x4*)(decb + (s + 1) * 128 + 16 * kt + 4 * q);
; #pragma unroll
;                 for (int j = 0; j < 4; ++j) { La[kt][j] = segb[(size_t)s * 8 * 2048 + (kt * 4 + j) * 64 + lane]; Lb[kt][j] = segb[(size_t)(s + 1) * 8 * 2048 + (kt * 4 + j) * 64 + lane]; } }
; #pragma unroll
;             for (int kt = 0; kt < 8; ++kt)
; #pragma unroll
;                 for (int j = 0; j < 4; ++j) S[kt][j] = __expf(Db[kt][j]) * (__expf(Da[kt][j]) * S[kt][j] + La[kt][j]) + Lb[kt][j];
;         }
;         if (s < seg) {
; #pragma unroll
;             for (int kt = 0; kt < 8; ++kt)
; #pragma unroll
;                 for (int j = 0; j < 4; ++j) S[kt][j] = __expf(decb[s * 128 + 16 * kt + 4 * q + j]) * S[kt][j] + segb[(size_t)s * 8 * 2048 + (kt * 4 + j) * 64 + lane];
;         }
;         f32x2 dtot = {0.f, 0.f};
;         bf16_t* Op = (bf16_t*)(p.ws + WS_O) + (size_t)dir * T * HW;
;         scan_run<true>(lds, Gp, Vp, Qp, Op, dir ? b * SEQ + SEQ - 1 : b * SEQ, dir ? -1 : 1, seg * 32, 32, dir * 1024 + h * 128, h * 128, S, dtot);
.LBB0_459:
	s_cmp_lt_i32 s60, 5
	s_cselect_b64 s[0:1], -1, 0
	s_cmp_gt_i32 s61, 4
	s_cselect_b64 s[2:3], -1, 0
	s_and_b64 s[0:1], s[0:1], s[2:3]
	s_andn2_b64 vcc, exec, s[0:1]
	s_cbranch_vccnz .LBB0_549
	s_cmpk_gt_i32 s12, 0xff
	s_cbranch_scc1 .LBB0_495
	v_readfirstlane_b32 s98, v242
	s_cmpk_gt_u32 s98, 0xff
	s_cbranch_scc0 .Lprio_scan2
	s_setprio 1
.Lprio_scan2:
	s_waitcnt lgkmcnt(0)
	s_add_u32 s26, s58, 0x23d86000
	s_addc_u32 s27, s59, 0
	s_add_u32 s28, s58, 0xfc86000
	s_addc_u32 s29, s59, 0
	s_add_u32 s30, s58, 0x13d86000
	v_and_b32_e32 v0, 63, v242
	s_addc_u32 s31, s59, 0
	s_add_i32 s0, 0, 0x13c00
	v_lshlrev_b32_e32 v3, 3, v0
	v_lshlrev_b32_e32 v5, 2, v0
	v_add_u32_e32 v85, s0, v3
	v_add_u32_e32 v87, 0, v5
	s_movk_i32 s0, 0x11c
	v_mad_u32_u24 v89, v0, s0, v87
	s_add_i32 s0, 0, 0x14c00
	v_add_u32_e32 v93, s0, v3
	s_add_i32 s0, 0, 0x14e00
	v_add_u32_e32 v146, s0, v3
	s_add_i32 s0, 0, 0x11800
	v_bfe_u32 v1, v242, 4, 2
	v_lshlrev_b32_e32 v9, 7, v242
	s_add_u32 s38, s58, 0x7a66000
	v_lshlrev_b32_e32 v80, 2, v1
	v_mov_b32_e32 v83, 0
	v_lshlrev_b32_e32 v2, 1, v242
	v_and_b32_e32 v81, 15, v242
	v_and_b32_e32 v84, 48, v242
	v_lshlrev_b32_e32 v1, 3, v1
	v_and_b32_e32 v82, 0x1e000, v9
	s_addc_u32 s39, s59, 0
	v_and_b32_e32 v2, 0x7e, v2
	v_lshlrev_b32_e32 v4, 1, v0
	v_add_u32_e32 v3, 0, v1
	v_mul_u32_u24_e32 v7, 0x110, v81
	v_add_u32_e32 v86, s0, v1
	v_add_u32_e32 v1, s0, v84
	v_mul_u32_u24_e32 v147, 0x90, v81
	v_or_b32_e32 v6, 0x3c0, v242
	v_or_b32_e32 v8, 0x7c0, v242
	v_lshl_add_u64 v[10:11], s[58:59], 0, v[82:83]
	s_mov_b64 s[2:3], 0x6a66000
	s_add_u32 s40, s58, 0x2bf86000
	v_lshlrev_b32_e32 v94, 2, v0
	s_mov_b32 s1, 0
	s_movk_i32 s34, 0x110
	v_add_u32_e32 v88, 0, v84
	s_movk_i32 s35, 0x90
	v_lshl_add_u64 v[90:91], v[10:11], 0, s[2:3]
	s_addc_u32 s41, s59, 0
	v_or_b32_e32 v92, v82, v5
	v_or_b32_e32 v148, 0x50, v81
	v_or_b32_e32 v149, 0x60, v81
	v_or_b32_e32 v150, 0x70, v81
	v_or_b32_e32 v151, 64, v81
	v_or_b32_e32 v152, 16, v81
	v_or_b32_e32 v153, 32, v81
	v_or_b32_e32 v154, 48, v81
	v_mov_b32_e32 v96, v94
	v_mov_b32_e32 v97, v83
	s_mov_b32 s42, 0x70000
	v_lshlrev_b32_e32 v98, 2, v6
	v_mov_b32_e32 v99, v83
	s_mov_b32 s43, 0x71000
	v_lshlrev_b32_e32 v100, 2, v8
	v_mov_b32_e32 v101, v83
	s_mov_b32 s44, 0x7a66000
	s_mov_b32 s45, 0x6a66000
	s_mov_b32 s46, 0x6a76000
	s_mov_b32 s47, 0x6a67000
	s_mov_b32 s48, 0x6a77000
	s_mov_b64 s[4:5], 0x20000
	s_mov_b64 s[6:7], 0x400
	s_movk_i32 s49, 0x1000
	v_lshlrev_b32_e32 v82, 1, v2
	v_lshlrev_b32_e32 v102, 1, v4
	v_lshlrev_b32_e32 v104, 1, v80
	s_mov_b32 s50, 0x5040100
	s_mov_b32 s51, 0x7060302
	v_add_u32_e32 v155, v3, v7
	v_add_u32_e32 v156, v1, v147
	s_mov_b32 s64, s12
	s_mov_b32 s65, s12
	s_branch .LBB0_463

; __device__ __forceinline__ unsigned xb_add(unsigned* p, unsigned v) { return __hip_atomic_fetch_add(p, v, __ATOMIC_RELAXED, __HIP_MEMORY_SCOPE_AGENT); }
; __device__ __forceinline__ void xcd_barrier(const XcdBarrier& b) {
;     asm volatile("s_waitcnt vmcnt(0)" ::: "memory");
;     __syncthreads();
;     if (threadIdx.x == 0) {
;         unsigned* bar = b.bar;
;         __builtin_amdgcn_s_waitcnt(0);
;         unsigned nloc = b.st[0], nx = b.st[1];
;         if (nloc == 0u) { xcd_barrier_complete(bar, b.x, nloc, nx); b.st[0] = nloc; b.st[1] = nx; }
;         const unsigned old = xb_add(&bar[XB_XSUB(b.x)], 1u);
.LBB0_495:
	s_setprio 0
	s_cmp_lt_i32 s61, 6
	s_cbranch_scc1 .LBB0_549
	s_waitcnt vmcnt(0)
	s_waitcnt vmcnt(0) lgkmcnt(0)
	s_barrier
	s_and_saveexec_b64 s[0:1], s[80:81]
	s_cbranch_execz .LBB0_548
	s_add_i32 s2, 0, 0x20000
	v_mov_b32_e32 v0, s2
	s_waitcnt vmcnt(0) expcnt(0) lgkmcnt(0)
	ds_read_b32 v2, v0
	s_add_i32 s2, 0, 0x20004
	v_mov_b32_e32 v0, s2
	ds_read_b32 v0, v0
	s_waitcnt lgkmcnt(1)
	v_cmp_ne_u32_e32 vcc, 0, v2
	s_cbranch_vccnz .LBB0_512
	s_add_u32 s2, s58, 0x35d86200
	s_addc_u32 s3, s59, 0
	s_add_u32 s4, s58, 0x35d86400
	s_addc_u32 s5, s59, 0
	s_add_u32 s6, s58, 0x35d86500
	s_addc_u32 s7, s59, 0
	s_add_u32 s8, s58, 0x35d86600
	s_addc_u32 s9, s59, 0
	s_add_u32 s20, s58, 0x35d86700
	s_addc_u32 s21, s59, 0
	s_add_u32 s26, s58, 0x35d86800
	s_addc_u32 s27, s59, 0
	s_add_u32 s28, s58, 0x35d86900
	s_addc_u32 s29, s59, 0
	s_add_u32 s30, s58, 0x35d86a00
	s_addc_u32 s31, s59, 0
	s_add_u32 s34, s58, 0x35d86b00
	s_addc_u32 s35, s59, 0
	s_add_u32 s38, s58, 0x35d86c00
	s_addc_u32 s39, s59, 0
	s_add_u32 s40, s58, 0x35d86d00
	s_addc_u32 s41, s59, 0
	s_add_u32 s42, s58, 0x35d86e00
	s_addc_u32 s43, s59, 0
	s_add_u32 s44, s58, 0x35d86f00
	s_addc_u32 s45, s59, 0
	s_add_u32 s46, s58, 0x35d87000
	s_addc_u32 s47, s59, 0
	s_add_u32 s48, s58, 0x35d87100
	s_addc_u32 s49, s59, 0
	s_add_u32 s50, s58, 0x35d87200
	s_addc_u32 s51, s59, 0
	s_mul_i32 s72, s63, s78
	s_add_u32 s64, s58, 0x35d87300
	s_mul_i32 s72, s72, s62
	s_addc_u32 s65, s59, 0
	s_mov_b32 s73, 1
	v_mov_b32_e32 v16, 0
	s_branch .LBB0_500
